# v24 with two s_nop 0 added in the MLA loop (VALU-write -> MFMA-read distance restored to 2 wait states before the first PV2 MFMA)
# speedup vs baseline: 1.0010x; 1.0010x over previous
.Lm_noload:
	s_cmp_gt_i32 s20, s35
	s_cbranch_scc1 .LBB0_379
	s_bitcmp1_b32 s20, 0
	s_cselect_b32 s38, 0xb400, 0
	v_add_u32_e32 v8, s38, v191
	ds_read_b128 v[10:13], v8
	ds_read_b128 v[14:17], v8 offset:32
	ds_read_b128 v[202:205], v8 offset:64
	ds_read_b128 v[206:209], v8 offset:96
	v_add_u32_e32 v197, s38, v196
	v_xor_b32_e32 v84, 0x80000000, v192
	v_mov_b32_e32 v85, v84
	v_mov_b32_e32 v86, v84
	v_mov_b32_e32 v87, v84
	v_mov_b32_e32 v88, v84
	v_mov_b32_e32 v89, v84
	v_mov_b32_e32 v90, v84
	v_mov_b32_e32 v91, v84
	v_mov_b32_e32 v92, v84
	v_mov_b32_e32 v93, v84
	v_mov_b32_e32 v94, v84
	v_mov_b32_e32 v95, v84
	v_mov_b32_e32 v96, v84
	v_mov_b32_e32 v97, v84
	v_mov_b32_e32 v98, v84
	v_mov_b32_e32 v99, v84
	s_setprio 3
	s_waitcnt lgkmcnt(3)
	s_nop 0
	v_mfma_f32_32x32x16_bf16 v[100:115], v[10:13], v[116:119], v[84:99]
	ds_read_b128 v[10:13], v8 offset:128
	s_waitcnt lgkmcnt(3)
	v_mfma_f32_32x32x16_bf16 v[100:115], v[14:17], v[120:123], v[100:115]
	ds_read_b128 v[14:17], v8 offset:160
	s_waitcnt lgkmcnt(3)
	v_mfma_f32_32x32x16_bf16 v[100:115], v[202:205], v[124:127], v[100:115]
	ds_read_b128 v[202:205], v8 offset:192
	s_waitcnt lgkmcnt(3)
	v_mfma_f32_32x32x16_bf16 v[100:115], v[206:209], v[132:135], v[100:115]
	ds_read_b128 v[206:209], v8 offset:224
	s_waitcnt lgkmcnt(3)
	v_mfma_f32_32x32x16_bf16 v[100:115], v[10:13], v[136:139], v[100:115]
	ds_read_b128 v[10:13], v8 offset:256
	s_waitcnt lgkmcnt(3)
	v_mfma_f32_32x32x16_bf16 v[100:115], v[14:17], v[140:143], v[100:115]
	ds_read_b128 v[14:17], v8 offset:288
	s_waitcnt lgkmcnt(3)
	v_mfma_f32_32x32x16_bf16 v[100:115], v[202:205], v[144:147], v[100:115]
	ds_read_b128 v[202:205], v8 offset:320
	s_waitcnt lgkmcnt(3)
	v_mfma_f32_32x32x16_bf16 v[100:115], v[206:209], v[148:151], v[100:115]
	ds_read_b128 v[206:209], v8 offset:352
	s_waitcnt lgkmcnt(3)
	v_mfma_f32_32x32x16_bf16 v[100:115], v[10:13], v[152:155], v[100:115]
	ds_read_b128 v[10:13], v8 offset:12800
	s_waitcnt lgkmcnt(3)
	v_mfma_f32_32x32x16_bf16 v[100:115], v[14:17], v[156:159], v[100:115]
	ds_read_b128 v[14:17], v8 offset:12832
	s_waitcnt lgkmcnt(3)
	v_mfma_f32_32x32x16_bf16 v[100:115], v[202:205], v[160:163], v[100:115]
	ds_read_b128 v[202:205], v8 offset:12864
	s_waitcnt lgkmcnt(3)
	v_mfma_f32_32x32x16_bf16 v[100:115], v[206:209], v[164:167], v[100:115]
	ds_read_b128 v[206:209], v8 offset:12896
	s_and_b64 vcc, exec, s[18:19]
	s_cbranch_vccz .Lm_p1
	s_setprio 0
	s_branch .Lm_pd

.Lm_contB:
	v_exp_f32_e32 v210, v84
	v_exp_f32_e32 v211, v85
	v_exp_f32_e32 v212, v86
	v_exp_f32_e32 v213, v87
	v_exp_f32_e32 v214, v88
	v_exp_f32_e32 v215, v89
	v_exp_f32_e32 v216, v90
	v_exp_f32_e32 v217, v91
	ds_read_b64_tr_b16 v[100:101], v197 offset:35840
	ds_read_b64_tr_b16 v[102:103], v197 offset:38400
	ds_read_b64_tr_b16 v[104:105], v197 offset:35904
	ds_read_b64_tr_b16 v[106:107], v197 offset:38464
	ds_read_b64_tr_b16 v[108:109], v197 offset:35968
	ds_read_b64_tr_b16 v[110:111], v197 offset:38528
	ds_read_b64_tr_b16 v[112:113], v197 offset:36032
	ds_read_b64_tr_b16 v[114:115], v197 offset:38592
	ds_read_b64_tr_b16 v[10:11], v197 offset:40960
	ds_read_b64_tr_b16 v[12:13], v197 offset:43520
	ds_read_b64_tr_b16 v[14:15], v197 offset:41024
	ds_read_b64_tr_b16 v[16:17], v197 offset:43584
	ds_read_b64_tr_b16 v[202:203], v197 offset:41088
	ds_read_b64_tr_b16 v[204:205], v197 offset:43648
	ds_read_b64_tr_b16 v[206:207], v197 offset:41152
	ds_read_b64_tr_b16 v[208:209], v197 offset:43712
	v_add_f32_e32 v240, 0, v210
	v_add_f32_e32 v240, v211, v240
	v_add_f32_e32 v240, v212, v240
	v_add_f32_e32 v240, v213, v240
	v_add_f32_e32 v240, v214, v240
	v_add_f32_e32 v240, v215, v240
	v_add_f32_e32 v240, v216, v240
	v_add_f32_e32 v240, v217, v240
	v_cvt_pk_bf16_f32 v226, v210, v211
	v_cvt_pk_bf16_f32 v227, v212, v213
	v_cvt_pk_bf16_f32 v228, v214, v215
	v_cvt_pk_bf16_f32 v229, v216, v217
	s_waitcnt lgkmcnt(14)
	s_nop 0
	v_mfma_f32_32x32x16_bf16 v[68:83], v[100:103], v[226:229], v[68:83]
	v_exp_f32_e32 v218, v92
	v_exp_f32_e32 v219, v93
	v_exp_f32_e32 v220, v94
	v_exp_f32_e32 v221, v95
	s_waitcnt lgkmcnt(12)
	v_mfma_f32_32x32x16_bf16 v[52:67], v[104:107], v[226:229], v[52:67]
	v_exp_f32_e32 v222, v96
	v_exp_f32_e32 v223, v97
	v_exp_f32_e32 v224, v98
	v_exp_f32_e32 v225, v99
	s_waitcnt lgkmcnt(10)
	v_mfma_f32_32x32x16_bf16 v[36:51], v[108:111], v[226:229], v[36:51]
	v_add_f32_e32 v240, v218, v240
	v_add_f32_e32 v240, v219, v240
	v_add_f32_e32 v240, v220, v240
	v_add_f32_e32 v240, v221, v240
	s_waitcnt lgkmcnt(8)
	v_mfma_f32_32x32x16_bf16 v[20:35], v[112:115], v[226:229], v[20:35]
	v_add_f32_e32 v240, v222, v240
	v_add_f32_e32 v240, v223, v240
	v_add_f32_e32 v240, v224, v240
	v_add_f32_e32 v240, v225, v240
	v_cvt_pk_bf16_f32 v230, v218, v219
	v_cvt_pk_bf16_f32 v231, v220, v221
	v_cvt_pk_bf16_f32 v232, v222, v223
	v_cvt_pk_bf16_f32 v233, v224, v225
	v_add_f32_e32 v193, v234, v240
	s_waitcnt lgkmcnt(6)
	v_mfma_f32_32x32x16_bf16 v[68:83], v[10:13], v[230:233], v[68:83]
	s_waitcnt lgkmcnt(4)
	v_mfma_f32_32x32x16_bf16 v[52:67], v[14:17], v[230:233], v[52:67]
	s_waitcnt lgkmcnt(2)
	v_mfma_f32_32x32x16_bf16 v[36:51], v[202:205], v[230:233], v[36:51]
	s_waitcnt lgkmcnt(0)
	v_mfma_f32_32x32x16_bf16 v[20:35], v[206:209], v[230:233], v[20:35]
